# out-proj loop: loader waves issue their 17 LDS-DMA per K-tile within the first 16 MFMAs (was 24)
# speedup vs baseline: 1.0026x; 1.0026x over previous
; DI f32x4 mfma16(bf16x8 a, bf16x8 b, f32x4 c) { return __builtin_amdgcn_mfma_f32_16x16x32_bf16(a, b, c, 0, 0, 0); }
; template <int N> DI void wait_vm() { asm volatile("s_waitcnt vmcnt(%0)" ::"n"(N) : "memory"); }
; DI void raw_barrier() { asm volatile("" ::: "memory"); __builtin_amdgcn_s_barrier(); asm volatile("" ::: "memory"); }
;     ...
;     auto compute = [&](int cb, bool do_issue, int ikt, int ib) {
;         const char* base = lds + cb * BUF;
;         bf16x8 af[MT], bfr[NT];
; #pragma unroll
;         for (int nt = 0; nt < NT; ++nt) {
;             const int br = BM + (nt / NTS) * (BN / NSEG) + wc * (NTS * 16) + (nt % NTS) * 16;
;             bfr[nt] = *(const bf16x8*)(base + (br + l15) * 64 + rsw);
;         }
; #pragma unroll
;         for (int mt = 0; mt < MT; ++mt) af[mt] = *(const bf16x8*)(base + (wr * WM + mt * 16 + l15) * 64 + rsw);
;         constexpr int TOT = MT * NT, PER = (TOT + NIT - 1) / NIT;
; #pragma unroll
;         for (int part = 0; part < NIT; ++part) {
; #pragma unroll
;             for (int q = 0; q < PER; ++q) {
;                 const int idx = part * PER + q;
;                 if (idx < TOT) {
;                     const int mt = idx / NT, nt = idx % NT;
;                     acc[mt][nt] = SWAP ? mfma16(bfr[nt], af[mt], acc[mt][nt]) : mfma16(af[mt], bfr[nt], acc[mt][nt]);
;                 }
;             }
;             __builtin_amdgcn_sched_barrier(0);
;             if (do_issue) issue_one(ikt, ib, part);
;             __builtin_amdgcn_sched_barrier(0);
;         }
;     };
;     __syncthreads();
; #pragma unroll
;     for (int d = 0; d < D; ++d) issue(d, d);
;     int cb = 0, ib = D;
;     for (int kt = 0; kt < KT; ++kt) {
;         if (D > 1 && kt + D - 1 < KT) wait_vm<(D - 1) * NIT>(); else wait_vm<0>();
;         raw_barrier();
;         compute(cb, kt + D < KT, kt + D, ib);
;         cb = (cb + 1 == NST) ? 0 : cb + 1;
;         ib = (ib + 1 == NST) ? 0 : ib + 1;
;     }
.Lpo1_s0d_2:
	v_mfma_f32_16x16x32_bf16 v[126:129], v[142:145], v[154:157], v[126:129]
	v_mfma_f32_16x16x32_bf16 v[122:125], v[150:153], v[154:157], v[122:125]
	s_add_u32 s6, s6, 0x2000
	s_addc_u32 s7, s7, 0
	s_add_u32 m0, m0, 0x2000
	s_nop 0
	global_load_lds_dwordx4 v199, s[6:7]
	global_load_lds_dwordx4 v199, s[6:7] offset:1024
	v_mfma_f32_16x16x32_bf16 v[118:121], v[158:161], v[154:157], v[118:121]
	v_mfma_f32_16x16x32_bf16 v[114:117], v[162:165], v[154:157], v[114:117]
	s_add_u32 s6, s6, 0x2000
	s_addc_u32 s7, s7, 0
	s_add_u32 m0, m0, 0x2000
	s_nop 0
	global_load_lds_dwordx4 v199, s[6:7]
	global_load_lds_dwordx4 v199, s[6:7] offset:1024
	v_mfma_f32_16x16x32_bf16 v[110:113], v[166:169], v[154:157], v[110:113]
	s_add_u32 s6, s6, 0x2000
	s_addc_u32 s7, s7, 0
	s_add_u32 m0, m0, 0x2000
	s_nop 0
	global_load_lds_dwordx4 v199, s[6:7]
	global_load_lds_dwordx4 v199, s[6:7] offset:1024
	v_mfma_f32_16x16x32_bf16 v[106:109], v[170:173], v[154:157], v[106:109]
	v_mfma_f32_16x16x32_bf16 v[102:105], v[174:177], v[154:157], v[102:105]
	s_add_u32 s6, s6, 0x2000
	s_addc_u32 s7, s7, 0
	s_add_u32 m0, m0, 0x2000
	s_nop 0
	global_load_lds_dwordx4 v199, s[6:7]
	global_load_lds_dwordx4 v199, s[6:7] offset:1024
	v_mfma_f32_16x16x32_bf16 v[66:69], v[178:181], v[154:157], v[66:69]
	ds_read_b128 v[154:157], v196 offset:1024
	v_mfma_f32_16x16x32_bf16 v[34:37], v[142:145], v[182:185], v[34:37]
	s_add_u32 s6, s6, 0x2000
	s_addc_u32 s7, s7, 0
	s_add_u32 m0, m0, 0x2000
	s_nop 0
	global_load_lds_dwordx4 v199, s[6:7]
	global_load_lds_dwordx4 v199, s[6:7] offset:1024
	v_mfma_f32_16x16x32_bf16 v[30:33], v[150:153], v[182:185], v[30:33]
	v_mfma_f32_16x16x32_bf16 v[26:29], v[158:161], v[182:185], v[26:29]
	s_add_u32 s6, s6, 0x2000
	s_addc_u32 s7, s7, 0
	s_add_u32 m0, m0, 0x2000
	s_nop 0
	global_load_lds_dwordx4 v199, s[6:7]
	global_load_lds_dwordx4 v199, s[6:7] offset:1024
	v_mfma_f32_16x16x32_bf16 v[22:25], v[162:165], v[182:185], v[22:25]
	s_add_u32 s6, s6, 0x2000
	s_addc_u32 s7, s7, 0
	s_add_u32 m0, m0, 0x2000
	s_nop 0
	global_load_lds_dwordx4 v199, s[6:7]
	global_load_lds_dwordx4 v199, s[6:7] offset:1024
	v_mfma_f32_16x16x32_bf16 v[18:21], v[166:169], v[182:185], v[18:21]
	v_mfma_f32_16x16x32_bf16 v[14:17], v[170:173], v[182:185], v[14:17]
	s_add_u32 s6, s6, 0x2000
	s_addc_u32 s7, s7, 0
	s_lshr_b32 s46, s40, 1
	s_bitcmp1_b32 s9, 0
	s_cselect_b32 m0, 0x11000, 0
	s_add_u32 m0, m0, s46
	s_add_u32 m0, m0, 0x10000
	s_nop 0
	global_load_lds_dwordx4 v0, s[6:7]
	v_mfma_f32_16x16x32_bf16 v[10:13], v[174:177], v[182:185], v[10:13]
	v_mfma_f32_16x16x32_bf16 v[6:9], v[178:181], v[182:185], v[6:9]
	ds_read_b128 v[182:185], v196 offset:2048
	v_mfma_f32_16x16x32_bf16 v[62:65], v[142:145], v[186:189], v[62:65]
	ds_read_b128 v[142:145], v197 offset:4096
	v_mfma_f32_16x16x32_bf16 v[58:61], v[150:153], v[186:189], v[58:61]
	ds_read_b128 v[150:153], v197 offset:5120
	v_mfma_f32_16x16x32_bf16 v[54:57], v[158:161], v[186:189], v[54:57]
	ds_read_b128 v[158:161], v197 offset:6144
	v_mfma_f32_16x16x32_bf16 v[50:53], v[162:165], v[186:189], v[50:53]
	ds_read_b128 v[162:165], v197 offset:7168
	v_mfma_f32_16x16x32_bf16 v[46:49], v[166:169], v[186:189], v[46:49]
	ds_read_b128 v[166:169], v197 offset:8192
	v_mfma_f32_16x16x32_bf16 v[42:45], v[170:173], v[186:189], v[42:45]
	ds_read_b128 v[170:173], v197 offset:9216
	v_mfma_f32_16x16x32_bf16 v[38:41], v[174:177], v[186:189], v[38:41]
	ds_read_b128 v[174:177], v197 offset:10240
	v_mfma_f32_16x16x32_bf16 v[2:5], v[178:181], v[186:189], v[2:5]
	ds_read_b128 v[178:181], v197 offset:11264
	ds_read_b128 v[186:189], v196 offset:3072
	s_add_i32 s9, s9, 1
	s_cmp_lg_u32 s9, 32
	s_cbranch_scc1 .Lpo1_l_loop
	s_waitcnt lgkmcnt(8)
	v_mfma_f32_16x16x32_bf16 v[98:101], v[142:145], v[146:149], v[98:101]
	s_waitcnt lgkmcnt(7)
	v_mfma_f32_16x16x32_bf16 v[94:97], v[150:153], v[146:149], v[94:97]
	s_waitcnt lgkmcnt(6)
	v_mfma_f32_16x16x32_bf16 v[90:93], v[158:161], v[146:149], v[90:93]
	s_waitcnt lgkmcnt(5)
	v_mfma_f32_16x16x32_bf16 v[86:89], v[162:165], v[146:149], v[86:89]
	s_waitcnt lgkmcnt(4)
	v_mfma_f32_16x16x32_bf16 v[82:85], v[166:169], v[146:149], v[82:85]
	s_waitcnt lgkmcnt(3)
	v_mfma_f32_16x16x32_bf16 v[78:81], v[170:173], v[146:149], v[78:81]
	s_waitcnt lgkmcnt(2)
	v_mfma_f32_16x16x32_bf16 v[74:77], v[174:177], v[146:149], v[74:77]
	s_waitcnt lgkmcnt(1)
	v_mfma_f32_16x16x32_bf16 v[70:73], v[178:181], v[146:149], v[70:73]
	s_waitcnt lgkmcnt(0)
	v_mfma_f32_16x16x32_bf16 v[126:129], v[142:145], v[154:157], v[126:129]
	v_mfma_f32_16x16x32_bf16 v[122:125], v[150:153], v[154:157], v[122:125]
	v_mfma_f32_16x16x32_bf16 v[118:121], v[158:161], v[154:157], v[118:121]
	v_mfma_f32_16x16x32_bf16 v[114:117], v[162:165], v[154:157], v[114:117]
	v_mfma_f32_16x16x32_bf16 v[110:113], v[166:169], v[154:157], v[110:113]
	v_mfma_f32_16x16x32_bf16 v[106:109], v[170:173], v[154:157], v[106:109]
	v_mfma_f32_16x16x32_bf16 v[102:105], v[174:177], v[154:157], v[102:105]
	v_mfma_f32_16x16x32_bf16 v[66:69], v[178:181], v[154:157], v[66:69]
	v_mfma_f32_16x16x32_bf16 v[34:37], v[142:145], v[182:185], v[34:37]
	v_mfma_f32_16x16x32_bf16 v[30:33], v[150:153], v[182:185], v[30:33]
	v_mfma_f32_16x16x32_bf16 v[26:29], v[158:161], v[182:185], v[26:29]
	v_mfma_f32_16x16x32_bf16 v[22:25], v[162:165], v[182:185], v[22:25]
	v_mfma_f32_16x16x32_bf16 v[18:21], v[166:169], v[182:185], v[18:21]
	v_mfma_f32_16x16x32_bf16 v[14:17], v[170:173], v[182:185], v[14:17]
	v_mfma_f32_16x16x32_bf16 v[10:13], v[174:177], v[182:185], v[10:13]
	v_mfma_f32_16x16x32_bf16 v[6:9], v[178:181], v[182:185], v[6:9]
	v_mfma_f32_16x16x32_bf16 v[62:65], v[142:145], v[186:189], v[62:65]
	v_mfma_f32_16x16x32_bf16 v[58:61], v[150:153], v[186:189], v[58:61]
	v_mfma_f32_16x16x32_bf16 v[54:57], v[158:161], v[186:189], v[54:57]
	v_mfma_f32_16x16x32_bf16 v[50:53], v[162:165], v[186:189], v[50:53]
	v_mfma_f32_16x16x32_bf16 v[46:49], v[166:169], v[186:189], v[46:49]
	v_mfma_f32_16x16x32_bf16 v[42:45], v[170:173], v[186:189], v[42:45]
	v_mfma_f32_16x16x32_bf16 v[38:41], v[174:177], v[186:189], v[38:41]
	v_mfma_f32_16x16x32_bf16 v[2:5], v[178:181], v[186:189], v[2:5]
	s_branch .Lpo1_join

; DI f32x4 mfma16(bf16x8 a, bf16x8 b, f32x4 c) { return __builtin_amdgcn_mfma_f32_16x16x32_bf16(a, b, c, 0, 0, 0); }
; template <int N> DI void wait_vm() { asm volatile("s_waitcnt vmcnt(%0)" ::"n"(N) : "memory"); }
; DI void raw_barrier() { asm volatile("" ::: "memory"); __builtin_amdgcn_s_barrier(); asm volatile("" ::: "memory"); }
;     ...
;     auto compute = [&](int cb, bool do_issue, int ikt, int ib) {
;         const char* base = lds + cb * BUF;
;         bf16x8 af[MT], bfr[NT];
; #pragma unroll
;         for (int nt = 0; nt < NT; ++nt) {
;             const int br = BM + (nt / NTS) * (BN / NSEG) + wc * (NTS * 16) + (nt % NTS) * 16;
;             bfr[nt] = *(const bf16x8*)(base + (br + l15) * 64 + rsw);
;         }
; #pragma unroll
;         for (int mt = 0; mt < MT; ++mt) af[mt] = *(const bf16x8*)(base + (wr * WM + mt * 16 + l15) * 64 + rsw);
;         constexpr int TOT = MT * NT, PER = (TOT + NIT - 1) / NIT;
; #pragma unroll
;         for (int part = 0; part < NIT; ++part) {
; #pragma unroll
;             for (int q = 0; q < PER; ++q) {
;                 const int idx = part * PER + q;
;                 if (idx < TOT) {
;                     const int mt = idx / NT, nt = idx % NT;
;                     acc[mt][nt] = SWAP ? mfma16(bfr[nt], af[mt], acc[mt][nt]) : mfma16(af[mt], bfr[nt], acc[mt][nt]);
;                 }
;             }
;             __builtin_amdgcn_sched_barrier(0);
;             if (do_issue) issue_one(ikt, ib, part);
;             __builtin_amdgcn_sched_barrier(0);
;         }
;     };
;     __syncthreads();
; #pragma unroll
;     for (int d = 0; d < D; ++d) issue(d, d);
;     int cb = 0, ib = D;
;     for (int kt = 0; kt < KT; ++kt) {
;         if (D > 1 && kt + D - 1 < KT) wait_vm<(D - 1) * NIT>(); else wait_vm<0>();
;         raw_barrier();
;         compute(cb, kt + D < KT, kt + D, ib);
;         cb = (cb + 1 == NST) ? 0 : cb + 1;
;         ib = (ib + 1 == NST) ? 0 : ib + 1;
;     }
.Lpo2_s0d_2:
	v_mfma_f32_16x16x32_bf16 v[126:129], v[142:145], v[154:157], v[126:129]
	v_mfma_f32_16x16x32_bf16 v[122:125], v[150:153], v[154:157], v[122:125]
	s_add_u32 s8, s8, 0x2000
	s_addc_u32 s9, s9, 0
	s_add_u32 m0, m0, 0x2000
	s_nop 0
	global_load_lds_dwordx4 v199, s[8:9]
	global_load_lds_dwordx4 v199, s[8:9] offset:1024
	v_mfma_f32_16x16x32_bf16 v[118:121], v[158:161], v[154:157], v[118:121]
	v_mfma_f32_16x16x32_bf16 v[114:117], v[162:165], v[154:157], v[114:117]
	s_add_u32 s8, s8, 0x2000
	s_addc_u32 s9, s9, 0
	s_add_u32 m0, m0, 0x2000
	s_nop 0
	global_load_lds_dwordx4 v199, s[8:9]
	global_load_lds_dwordx4 v199, s[8:9] offset:1024
	v_mfma_f32_16x16x32_bf16 v[110:113], v[166:169], v[154:157], v[110:113]
	s_add_u32 s8, s8, 0x2000
	s_addc_u32 s9, s9, 0
	s_add_u32 m0, m0, 0x2000
	s_nop 0
	global_load_lds_dwordx4 v199, s[8:9]
	global_load_lds_dwordx4 v199, s[8:9] offset:1024
	v_mfma_f32_16x16x32_bf16 v[106:109], v[170:173], v[154:157], v[106:109]
	v_mfma_f32_16x16x32_bf16 v[102:105], v[174:177], v[154:157], v[102:105]
	s_add_u32 s8, s8, 0x2000
	s_addc_u32 s9, s9, 0
	s_add_u32 m0, m0, 0x2000
	s_nop 0
	global_load_lds_dwordx4 v199, s[8:9]
	global_load_lds_dwordx4 v199, s[8:9] offset:1024
	v_mfma_f32_16x16x32_bf16 v[66:69], v[178:181], v[154:157], v[66:69]
	ds_read_b128 v[154:157], v196 offset:1024
	v_mfma_f32_16x16x32_bf16 v[34:37], v[142:145], v[182:185], v[34:37]
	s_add_u32 s8, s8, 0x2000
	s_addc_u32 s9, s9, 0
	s_add_u32 m0, m0, 0x2000
	s_nop 0
	global_load_lds_dwordx4 v199, s[8:9]
	global_load_lds_dwordx4 v199, s[8:9] offset:1024
	v_mfma_f32_16x16x32_bf16 v[30:33], v[150:153], v[182:185], v[30:33]
	v_mfma_f32_16x16x32_bf16 v[26:29], v[158:161], v[182:185], v[26:29]
	s_add_u32 s8, s8, 0x2000
	s_addc_u32 s9, s9, 0
	s_add_u32 m0, m0, 0x2000
	s_nop 0
	global_load_lds_dwordx4 v199, s[8:9]
	global_load_lds_dwordx4 v199, s[8:9] offset:1024
	v_mfma_f32_16x16x32_bf16 v[22:25], v[162:165], v[182:185], v[22:25]
	s_add_u32 s8, s8, 0x2000
	s_addc_u32 s9, s9, 0
	s_add_u32 m0, m0, 0x2000
	s_nop 0
	global_load_lds_dwordx4 v199, s[8:9]
	global_load_lds_dwordx4 v199, s[8:9] offset:1024
	v_mfma_f32_16x16x32_bf16 v[18:21], v[166:169], v[182:185], v[18:21]
	v_mfma_f32_16x16x32_bf16 v[14:17], v[170:173], v[182:185], v[14:17]
	s_add_u32 s8, s8, 0x2000
	s_addc_u32 s9, s9, 0
	s_lshr_b32 s46, s40, 1
	s_bitcmp1_b32 s29, 0
	s_cselect_b32 m0, 0x11000, 0
	s_add_u32 m0, m0, s46
	s_add_u32 m0, m0, 0x10000
	s_nop 0
	global_load_lds_dwordx4 v0, s[8:9]
	v_mfma_f32_16x16x32_bf16 v[10:13], v[174:177], v[182:185], v[10:13]
	v_mfma_f32_16x16x32_bf16 v[6:9], v[178:181], v[182:185], v[6:9]
	ds_read_b128 v[182:185], v196 offset:2048
	v_mfma_f32_16x16x32_bf16 v[62:65], v[142:145], v[186:189], v[62:65]
	ds_read_b128 v[142:145], v197 offset:4096
	v_mfma_f32_16x16x32_bf16 v[58:61], v[150:153], v[186:189], v[58:61]
	ds_read_b128 v[150:153], v197 offset:5120
	v_mfma_f32_16x16x32_bf16 v[54:57], v[158:161], v[186:189], v[54:57]
	ds_read_b128 v[158:161], v197 offset:6144
	v_mfma_f32_16x16x32_bf16 v[50:53], v[162:165], v[186:189], v[50:53]
	ds_read_b128 v[162:165], v197 offset:7168
	v_mfma_f32_16x16x32_bf16 v[46:49], v[166:169], v[186:189], v[46:49]
	ds_read_b128 v[166:169], v197 offset:8192
	v_mfma_f32_16x16x32_bf16 v[42:45], v[170:173], v[186:189], v[42:45]
	ds_read_b128 v[170:173], v197 offset:9216
	v_mfma_f32_16x16x32_bf16 v[38:41], v[174:177], v[186:189], v[38:41]
	ds_read_b128 v[174:177], v197 offset:10240
	v_mfma_f32_16x16x32_bf16 v[2:5], v[178:181], v[186:189], v[2:5]
	ds_read_b128 v[178:181], v197 offset:11264
	ds_read_b128 v[186:189], v196 offset:3072
	s_add_i32 s29, s29, 1
	s_cmp_lg_u32 s29, 32
	s_cbranch_scc1 .Lpo2_l_loop
	s_waitcnt lgkmcnt(8)
	v_mfma_f32_16x16x32_bf16 v[98:101], v[142:145], v[146:149], v[98:101]
	s_waitcnt lgkmcnt(7)
	v_mfma_f32_16x16x32_bf16 v[94:97], v[150:153], v[146:149], v[94:97]
	s_waitcnt lgkmcnt(6)
	v_mfma_f32_16x16x32_bf16 v[90:93], v[158:161], v[146:149], v[90:93]
	s_waitcnt lgkmcnt(5)
	v_mfma_f32_16x16x32_bf16 v[86:89], v[162:165], v[146:149], v[86:89]
	s_waitcnt lgkmcnt(4)
	v_mfma_f32_16x16x32_bf16 v[82:85], v[166:169], v[146:149], v[82:85]
	s_waitcnt lgkmcnt(3)
	v_mfma_f32_16x16x32_bf16 v[78:81], v[170:173], v[146:149], v[78:81]
	s_waitcnt lgkmcnt(2)
	v_mfma_f32_16x16x32_bf16 v[74:77], v[174:177], v[146:149], v[74:77]
	s_waitcnt lgkmcnt(1)
	v_mfma_f32_16x16x32_bf16 v[70:73], v[178:181], v[146:149], v[70:73]
	s_waitcnt lgkmcnt(0)
	v_mfma_f32_16x16x32_bf16 v[126:129], v[142:145], v[154:157], v[126:129]
	v_mfma_f32_16x16x32_bf16 v[122:125], v[150:153], v[154:157], v[122:125]
	v_mfma_f32_16x16x32_bf16 v[118:121], v[158:161], v[154:157], v[118:121]
	v_mfma_f32_16x16x32_bf16 v[114:117], v[162:165], v[154:157], v[114:117]
	v_mfma_f32_16x16x32_bf16 v[110:113], v[166:169], v[154:157], v[110:113]
	v_mfma_f32_16x16x32_bf16 v[106:109], v[170:173], v[154:157], v[106:109]
	v_mfma_f32_16x16x32_bf16 v[102:105], v[174:177], v[154:157], v[102:105]
	v_mfma_f32_16x16x32_bf16 v[66:69], v[178:181], v[154:157], v[66:69]
	v_mfma_f32_16x16x32_bf16 v[34:37], v[142:145], v[182:185], v[34:37]
	v_mfma_f32_16x16x32_bf16 v[30:33], v[150:153], v[182:185], v[30:33]
	v_mfma_f32_16x16x32_bf16 v[26:29], v[158:161], v[182:185], v[26:29]
	v_mfma_f32_16x16x32_bf16 v[22:25], v[162:165], v[182:185], v[22:25]
	v_mfma_f32_16x16x32_bf16 v[18:21], v[166:169], v[182:185], v[18:21]
	v_mfma_f32_16x16x32_bf16 v[14:17], v[170:173], v[182:185], v[14:17]
	v_mfma_f32_16x16x32_bf16 v[10:13], v[174:177], v[182:185], v[10:13]
	v_mfma_f32_16x16x32_bf16 v[6:9], v[178:181], v[182:185], v[6:9]
	v_mfma_f32_16x16x32_bf16 v[62:65], v[142:145], v[186:189], v[62:65]
	v_mfma_f32_16x16x32_bf16 v[58:61], v[150:153], v[186:189], v[58:61]
	v_mfma_f32_16x16x32_bf16 v[54:57], v[158:161], v[186:189], v[54:57]
	v_mfma_f32_16x16x32_bf16 v[50:53], v[162:165], v[186:189], v[50:53]
	v_mfma_f32_16x16x32_bf16 v[46:49], v[166:169], v[186:189], v[46:49]
	v_mfma_f32_16x16x32_bf16 v[42:45], v[170:173], v[186:189], v[42:45]
	v_mfma_f32_16x16x32_bf16 v[38:41], v[174:177], v[186:189], v[38:41]
	v_mfma_f32_16x16x32_bf16 v[2:5], v[178:181], v[186:189], v[2:5]
	s_branch .Lpo2_join
